# phase 3 shared-rotary-key tiles: hand-written epilogue, rotated key through LDS transpose, 32 dwordx4 stores per wave instead of 256 short stores
# baseline (speedup 1.0000x reference)
.LBB0_1112:
	s_cmp_lt_i32 s40, 0
	s_cbranch_scc1 .LBB0_1111
	v_mov_b32_e32 v0, v161
	v_mov_b32_e32 v31, v186
	s_add_i32 s12, s41, 0xffffe000
	s_mov_b32 s13, s77
	s_lshl_b64 s[78:79], s[12:13], 11
	v_lshlrev_b32_e32 v1, 4, v31
	v_ashrrev_i32_e32 v32, 3, v31
	v_and_b32_e32 v30, 0x70, v1
	s_add_u32 vcc_lo, s39, s78
	v_readlane_b32 s13, v254, 36
	v_lshl_or_b32 v34, v32, 11, v30
	s_addc_u32 vcc_hi, s13, s79
	v_add_u32_e32 v35, 0x10000, v34
	v_add_u32_e32 v38, 0x20000, v34
	v_add_u32_e32 v39, 0x30000, v34
	s_barrier
	global_load_dwordx4 v[14:17], v34, vcc
	global_load_dwordx4 v[18:21], v35, vcc
	global_load_dwordx4 v[22:25], v38, vcc
	global_load_dwordx4 v[26:29], v39, vcc
	global_load_dwordx4 v[46:49], v34, s[10:11]
	global_load_dwordx4 v[50:53], v35, s[10:11]
	v_lshrrev_b32_e32 v33, 1, v31
	v_and_b32_e32 v31, 31, v31
	v_and_or_b32 v45, v33, 32, v31
	v_and_or_b32 v31, v33, s44, v31
	v_and_b32_e32 v78, 16, v33
	v_mad_u64_u32 v[32:33], s[78:79], v32, s43, v[30:31]
	v_mad_u64_u32 v[36:37], s[78:79], v31, s43, v[78:79]
	v_mad_u32_u24 v33, v45, s43, v78
	v_mov_b32_e32 v1, v0
	v_mov_b32_e32 v2, v0
	v_mov_b32_e32 v3, v0
	v_mov_b32_e32 v4, v0
	v_mov_b32_e32 v5, v0
	v_mov_b32_e32 v6, v0
	v_mov_b32_e32 v7, v0
	s_waitcnt vmcnt(6)
	v_mov_b32_e32 v8, v0
	v_mov_b32_e32 v9, v0
	v_mov_b32_e32 v10, v0
	v_mov_b32_e32 v11, v0
	v_mov_b32_e32 v12, v0
	v_mov_b32_e32 v13, v0
	s_waitcnt vmcnt(5)
	ds_write_b128 v32, v[14:17]
	s_waitcnt vmcnt(4)
	ds_write_b128 v32, v[18:21] offset:4608
	s_waitcnt vmcnt(3)
	ds_write_b128 v32, v[22:25] offset:9216
	s_waitcnt vmcnt(2)
	ds_write_b128 v32, v[26:29] offset:13824
	s_waitcnt vmcnt(1)
	ds_write_b128 v32, v[46:49] offset:36864
	s_waitcnt vmcnt(0)
	ds_write_b128 v32, v[50:53] offset:41472
	global_load_dwordx4 v[46:49], v34, vcc offset:128
	global_load_dwordx4 v[50:53], v35, vcc offset:128
	global_load_dwordx4 v[58:61], v38, vcc offset:128
	global_load_dwordx4 v[62:65], v39, vcc offset:128
	global_load_dwordx4 v[66:69], v34, s[18:19]
	global_load_dwordx4 v[70:73], v35, s[18:19]
	s_waitcnt lgkmcnt(0)
	s_barrier
	ds_read_b128 v[74:77], v36
	ds_read_b128 v[78:81], v36 offset:4608
	ds_read_b128 v[82:85], v36 offset:32
	ds_read_b128 v[86:89], v33 offset:36864
	v_mov_b32_e32 v14, v0
	v_mov_b32_e32 v15, v0
	ds_read_b128 v[90:93], v36 offset:4640
	ds_read_b128 v[94:97], v33 offset:36896
	s_waitcnt lgkmcnt(2)
	v_mfma_f32_32x32x16_bf16 v[16:31], v[74:77], v[86:89], v[0:15]
	v_mfma_f32_32x32x16_bf16 v[0:15], v[78:81], v[86:89], v[0:15]
	s_waitcnt lgkmcnt(0)
	v_mfma_f32_32x32x16_bf16 v[16:31], v[82:85], v[94:97], v[16:31]
	v_mfma_f32_32x32x16_bf16 v[0:15], v[90:93], v[94:97], v[0:15]
	ds_read_b128 v[74:77], v36 offset:64
	ds_read_b128 v[82:85], v36 offset:4672
	ds_read_b128 v[78:81], v33 offset:36928
	s_waitcnt lgkmcnt(0)
	v_mfma_f32_32x32x16_bf16 v[16:31], v[74:77], v[78:81], v[16:31]
	v_mfma_f32_32x32x16_bf16 v[0:15], v[82:85], v[78:81], v[0:15]
	global_load_dwordx4 v[74:77], v34, vcc offset:256
	global_load_dwordx4 v[78:81], v35, vcc offset:256
	global_load_dwordx4 v[82:85], v38, vcc offset:256
	global_load_dwordx4 v[86:89], v39, vcc offset:256
	global_load_dwordx4 v[90:93], v34, s[20:21]
	global_load_dwordx4 v[94:97], v35, s[20:21]
	s_waitcnt vmcnt(11)
	ds_write_b128 v32, v[46:49] offset:18432
	s_waitcnt vmcnt(10)
	ds_write_b128 v32, v[50:53] offset:23040
	s_waitcnt vmcnt(9)
	ds_write_b128 v32, v[58:61] offset:27648
	s_waitcnt vmcnt(8)
	ds_write_b128 v32, v[62:65] offset:32256
	ds_read_b128 v[46:49], v36 offset:96
	ds_read_b128 v[58:61], v36 offset:4704
	ds_read_b128 v[50:53], v33 offset:36960
	s_waitcnt vmcnt(7)
	ds_write_b128 v32, v[66:69] offset:46080
	s_waitcnt vmcnt(6)
	ds_write_b128 v32, v[70:73] offset:50688
	s_waitcnt lgkmcnt(2)
	v_mfma_f32_32x32x16_bf16 v[16:31], v[46:49], v[50:53], v[16:31]
	s_waitcnt lgkmcnt(0)
	s_barrier
	v_mfma_f32_32x32x16_bf16 v[0:15], v[58:61], v[50:53], v[0:15]
	ds_read_b128 v[46:49], v36 offset:18432
	ds_read_b128 v[58:61], v36 offset:23040
	ds_read_b128 v[50:53], v33 offset:46080
	ds_read_b128 v[62:65], v36 offset:18464
	ds_read_b128 v[66:69], v36 offset:23072
	ds_read_b128 v[70:73], v33 offset:46112
	s_waitcnt lgkmcnt(3)
	v_mfma_f32_32x32x16_bf16 v[16:31], v[46:49], v[50:53], v[16:31]
	v_mfma_f32_32x32x16_bf16 v[0:15], v[58:61], v[50:53], v[0:15]
	global_load_dwordx4 v[46:49], v34, vcc offset:384
	global_load_dwordx4 v[50:53], v35, vcc offset:384
	global_load_dwordx4 v[58:61], v38, vcc offset:384
	global_load_dwordx4 v[98:101], v39, vcc offset:384
	global_load_dwordx4 v[102:105], v34, s[22:23]
	global_load_dwordx4 v[106:109], v35, s[22:23]
	ds_read_b128 v[110:113], v36 offset:18496
	ds_read_b128 v[114:117], v36 offset:23104
	ds_read_b128 v[118:121], v33 offset:46144
	s_waitcnt vmcnt(11)
	ds_write_b128 v32, v[74:77]
	s_waitcnt vmcnt(10)
	ds_write_b128 v32, v[78:81] offset:4608
	s_waitcnt vmcnt(9)
	ds_write_b128 v32, v[82:85] offset:9216
	s_waitcnt vmcnt(8)
	ds_write_b128 v32, v[86:89] offset:13824
	s_waitcnt lgkmcnt(7)
	v_mfma_f32_32x32x16_bf16 v[16:31], v[62:65], v[70:73], v[16:31]
	v_mfma_f32_32x32x16_bf16 v[0:15], v[66:69], v[70:73], v[0:15]
	ds_read_b128 v[62:65], v36 offset:18528
	ds_read_b128 v[66:69], v36 offset:23136
	ds_read_b128 v[70:73], v33 offset:46176
	s_waitcnt vmcnt(7)
	ds_write_b128 v32, v[90:93] offset:36864
	s_waitcnt vmcnt(6)
	ds_write_b128 v32, v[94:97] offset:41472
	s_waitcnt lgkmcnt(0)
	s_barrier
	v_mfma_f32_32x32x16_bf16 v[16:31], v[110:113], v[118:121], v[16:31]
	v_mfma_f32_32x32x16_bf16 v[0:15], v[114:117], v[118:121], v[0:15]
	v_mfma_f32_32x32x16_bf16 v[16:31], v[62:65], v[70:73], v[16:31]
	v_mfma_f32_32x32x16_bf16 v[0:15], v[66:69], v[70:73], v[0:15]
	ds_read_b128 v[62:65], v36
	ds_read_b128 v[70:73], v36 offset:4608
	ds_read_b128 v[66:69], v33 offset:36864
	ds_read_b128 v[74:77], v36 offset:32
	ds_read_b128 v[78:81], v36 offset:4640
	ds_read_b128 v[82:85], v33 offset:36896
	s_waitcnt lgkmcnt(3)
	v_mfma_f32_32x32x16_bf16 v[16:31], v[62:65], v[66:69], v[16:31]
	v_mfma_f32_32x32x16_bf16 v[0:15], v[70:73], v[66:69], v[0:15]
	global_load_dwordx4 v[62:65], v34, vcc offset:512
	global_load_dwordx4 v[66:69], v35, vcc offset:512
	global_load_dwordx4 v[70:73], v38, vcc offset:512
	global_load_dwordx4 v[86:89], v39, vcc offset:512
	global_load_dwordx4 v[90:93], v34, s[24:25]
	global_load_dwordx4 v[94:97], v35, s[24:25]
	ds_read_b128 v[110:113], v36 offset:64
	ds_read_b128 v[114:117], v36 offset:4672
	ds_read_b128 v[118:121], v33 offset:36928
	s_waitcnt vmcnt(11)
	ds_write_b128 v32, v[46:49] offset:18432
	s_waitcnt vmcnt(10)
	ds_write_b128 v32, v[50:53] offset:23040
	s_waitcnt vmcnt(9)
	ds_write_b128 v32, v[58:61] offset:27648
	s_waitcnt vmcnt(8)
	ds_write_b128 v32, v[98:101] offset:32256
	s_waitcnt lgkmcnt(7)
	v_mfma_f32_32x32x16_bf16 v[16:31], v[74:77], v[82:85], v[16:31]
	v_mfma_f32_32x32x16_bf16 v[0:15], v[78:81], v[82:85], v[0:15]
	ds_read_b128 v[46:49], v36 offset:96
	ds_read_b128 v[50:53], v36 offset:4704
	ds_read_b128 v[58:61], v33 offset:36960
	s_waitcnt vmcnt(7)
	ds_write_b128 v32, v[102:105] offset:46080
	s_waitcnt vmcnt(6)
	ds_write_b128 v32, v[106:109] offset:50688
	s_waitcnt lgkmcnt(0)
	s_barrier
	v_mfma_f32_32x32x16_bf16 v[16:31], v[110:113], v[118:121], v[16:31]
	v_mfma_f32_32x32x16_bf16 v[0:15], v[114:117], v[118:121], v[0:15]
	v_mfma_f32_32x32x16_bf16 v[16:31], v[46:49], v[58:61], v[16:31]
	v_mfma_f32_32x32x16_bf16 v[0:15], v[50:53], v[58:61], v[0:15]
	ds_read_b128 v[46:49], v36 offset:18432
	ds_read_b128 v[58:61], v36 offset:23040
	ds_read_b128 v[50:53], v33 offset:46080
	ds_read_b128 v[74:77], v36 offset:18464
	ds_read_b128 v[78:81], v36 offset:23072
	ds_read_b128 v[82:85], v33 offset:46112
	s_waitcnt lgkmcnt(3)
	v_mfma_f32_32x32x16_bf16 v[16:31], v[46:49], v[50:53], v[16:31]
	v_mfma_f32_32x32x16_bf16 v[0:15], v[58:61], v[50:53], v[0:15]
	global_load_dwordx4 v[46:49], v34, vcc offset:640
	global_load_dwordx4 v[50:53], v35, vcc offset:640
	global_load_dwordx4 v[58:61], v38, vcc offset:640
	global_load_dwordx4 v[98:101], v39, vcc offset:640
	global_load_dwordx4 v[102:105], v34, s[26:27]
	global_load_dwordx4 v[106:109], v35, s[26:27]
	ds_read_b128 v[110:113], v36 offset:18496
	ds_read_b128 v[114:117], v36 offset:23104
	ds_read_b128 v[118:121], v33 offset:46144
	s_waitcnt vmcnt(11)
	ds_write_b128 v32, v[62:65]
	s_waitcnt vmcnt(10)
	ds_write_b128 v32, v[66:69] offset:4608
	s_waitcnt vmcnt(9)
	ds_write_b128 v32, v[70:73] offset:9216
	s_waitcnt vmcnt(8)
	ds_write_b128 v32, v[86:89] offset:13824
	s_waitcnt lgkmcnt(7)
	v_mfma_f32_32x32x16_bf16 v[16:31], v[74:77], v[82:85], v[16:31]
	v_mfma_f32_32x32x16_bf16 v[0:15], v[78:81], v[82:85], v[0:15]
	ds_read_b128 v[62:65], v36 offset:18528
	ds_read_b128 v[66:69], v36 offset:23136
	ds_read_b128 v[70:73], v33 offset:46176
	s_waitcnt vmcnt(7)
	ds_write_b128 v32, v[90:93] offset:36864
	s_waitcnt vmcnt(6)
	ds_write_b128 v32, v[94:97] offset:41472
	s_waitcnt lgkmcnt(0)
	s_barrier
	v_mfma_f32_32x32x16_bf16 v[16:31], v[110:113], v[118:121], v[16:31]
	v_mfma_f32_32x32x16_bf16 v[0:15], v[114:117], v[118:121], v[0:15]
	v_mfma_f32_32x32x16_bf16 v[16:31], v[62:65], v[70:73], v[16:31]
	v_mfma_f32_32x32x16_bf16 v[0:15], v[66:69], v[70:73], v[0:15]
	ds_read_b128 v[62:65], v36
	ds_read_b128 v[70:73], v36 offset:4608
	ds_read_b128 v[66:69], v33 offset:36864
	ds_read_b128 v[74:77], v36 offset:32
	ds_read_b128 v[78:81], v36 offset:4640
	ds_read_b128 v[82:85], v33 offset:36896
	s_waitcnt lgkmcnt(3)
	v_mfma_f32_32x32x16_bf16 v[16:31], v[62:65], v[66:69], v[16:31]
	v_mfma_f32_32x32x16_bf16 v[0:15], v[70:73], v[66:69], v[0:15]
	global_load_dwordx4 v[62:65], v34, vcc offset:768
	global_load_dwordx4 v[66:69], v35, vcc offset:768
	global_load_dwordx4 v[70:73], v38, vcc offset:768
	global_load_dwordx4 v[86:89], v39, vcc offset:768
	global_load_dwordx4 v[90:93], v34, s[28:29]
	global_load_dwordx4 v[94:97], v35, s[28:29]
	ds_read_b128 v[110:113], v36 offset:64
	ds_read_b128 v[114:117], v36 offset:4672
	ds_read_b128 v[118:121], v33 offset:36928
	s_waitcnt vmcnt(11)
	ds_write_b128 v32, v[46:49] offset:18432
	s_waitcnt vmcnt(10)
	ds_write_b128 v32, v[50:53] offset:23040
	s_waitcnt vmcnt(9)
	ds_write_b128 v32, v[58:61] offset:27648
	s_waitcnt vmcnt(8)
	ds_write_b128 v32, v[98:101] offset:32256
	s_waitcnt lgkmcnt(7)
	v_mfma_f32_32x32x16_bf16 v[16:31], v[74:77], v[82:85], v[16:31]
	v_mfma_f32_32x32x16_bf16 v[0:15], v[78:81], v[82:85], v[0:15]
	ds_read_b128 v[46:49], v36 offset:96
	ds_read_b128 v[50:53], v36 offset:4704
	ds_read_b128 v[58:61], v33 offset:36960
	s_waitcnt vmcnt(7)
	ds_write_b128 v32, v[102:105] offset:46080
	s_waitcnt vmcnt(6)
	ds_write_b128 v32, v[106:109] offset:50688
	s_waitcnt lgkmcnt(0)
	s_barrier
	v_mfma_f32_32x32x16_bf16 v[16:31], v[110:113], v[118:121], v[16:31]
	v_mfma_f32_32x32x16_bf16 v[0:15], v[114:117], v[118:121], v[0:15]
	v_mfma_f32_32x32x16_bf16 v[16:31], v[46:49], v[58:61], v[16:31]
	v_mfma_f32_32x32x16_bf16 v[0:15], v[50:53], v[58:61], v[0:15]
	ds_read_b128 v[46:49], v36 offset:18432
	ds_read_b128 v[58:61], v36 offset:23040
	ds_read_b128 v[50:53], v33 offset:46080
	ds_read_b128 v[74:77], v36 offset:18464
	ds_read_b128 v[78:81], v36 offset:23072
	ds_read_b128 v[82:85], v33 offset:46112
	s_waitcnt lgkmcnt(3)
	v_mfma_f32_32x32x16_bf16 v[16:31], v[46:49], v[50:53], v[16:31]
	v_mfma_f32_32x32x16_bf16 v[0:15], v[58:61], v[50:53], v[0:15]
	global_load_dwordx4 v[46:49], v34, vcc offset:896
	global_load_dwordx4 v[50:53], v35, vcc offset:896
	global_load_dwordx4 v[58:61], v38, vcc offset:896
	global_load_dwordx4 v[98:101], v39, vcc offset:896
	global_load_dwordx4 v[102:105], v34, s[30:31]
	global_load_dwordx4 v[106:109], v35, s[30:31]
	ds_read_b128 v[110:113], v36 offset:18496
	ds_read_b128 v[114:117], v36 offset:23104
	ds_read_b128 v[118:121], v33 offset:46144
	s_waitcnt vmcnt(11)
	ds_write_b128 v32, v[62:65]
	s_waitcnt vmcnt(10)
	ds_write_b128 v32, v[66:69] offset:4608
	s_waitcnt vmcnt(9)
	ds_write_b128 v32, v[70:73] offset:9216
	s_waitcnt vmcnt(8)
	ds_write_b128 v32, v[86:89] offset:13824
	s_waitcnt lgkmcnt(7)
	v_mfma_f32_32x32x16_bf16 v[16:31], v[74:77], v[82:85], v[16:31]
	v_mfma_f32_32x32x16_bf16 v[0:15], v[78:81], v[82:85], v[0:15]
	ds_read_b128 v[62:65], v36 offset:18528
	ds_read_b128 v[66:69], v36 offset:23136
	ds_read_b128 v[70:73], v33 offset:46176
	s_waitcnt vmcnt(7)
	ds_write_b128 v32, v[90:93] offset:36864
	s_waitcnt vmcnt(6)
	ds_write_b128 v32, v[94:97] offset:41472
	s_waitcnt lgkmcnt(0)
	s_barrier
	v_mfma_f32_32x32x16_bf16 v[16:31], v[110:113], v[118:121], v[16:31]
	v_mfma_f32_32x32x16_bf16 v[0:15], v[114:117], v[118:121], v[0:15]
	v_mfma_f32_32x32x16_bf16 v[16:31], v[62:65], v[70:73], v[16:31]
	v_mfma_f32_32x32x16_bf16 v[0:15], v[66:69], v[70:73], v[0:15]
	ds_read_b128 v[62:65], v36
	ds_read_b128 v[70:73], v36 offset:4608
	ds_read_b128 v[66:69], v33 offset:36864
	ds_read_b128 v[74:77], v36 offset:32
	ds_read_b128 v[78:81], v36 offset:4640
	ds_read_b128 v[82:85], v33 offset:36896
	s_waitcnt lgkmcnt(3)
	v_mfma_f32_32x32x16_bf16 v[16:31], v[62:65], v[66:69], v[16:31]
	v_mfma_f32_32x32x16_bf16 v[0:15], v[70:73], v[66:69], v[0:15]
	global_load_dwordx4 v[62:65], v34, vcc offset:1024
	global_load_dwordx4 v[66:69], v35, vcc offset:1024
	global_load_dwordx4 v[70:73], v38, vcc offset:1024
	global_load_dwordx4 v[86:89], v39, vcc offset:1024
	global_load_dwordx4 v[90:93], v34, s[34:35]
	global_load_dwordx4 v[94:97], v35, s[34:35]
	ds_read_b128 v[110:113], v36 offset:64
	ds_read_b128 v[114:117], v36 offset:4672
	ds_read_b128 v[118:121], v33 offset:36928
	s_waitcnt vmcnt(11)
	ds_write_b128 v32, v[46:49] offset:18432
	s_waitcnt vmcnt(10)
	ds_write_b128 v32, v[50:53] offset:23040
	s_waitcnt vmcnt(9)
	ds_write_b128 v32, v[58:61] offset:27648
	s_waitcnt vmcnt(8)
	ds_write_b128 v32, v[98:101] offset:32256
	s_waitcnt lgkmcnt(7)
	v_mfma_f32_32x32x16_bf16 v[16:31], v[74:77], v[82:85], v[16:31]
	v_mfma_f32_32x32x16_bf16 v[0:15], v[78:81], v[82:85], v[0:15]
	ds_read_b128 v[46:49], v36 offset:96
	ds_read_b128 v[50:53], v36 offset:4704
	ds_read_b128 v[58:61], v33 offset:36960
	s_waitcnt vmcnt(7)
	ds_write_b128 v32, v[102:105] offset:46080
	s_waitcnt vmcnt(6)
	ds_write_b128 v32, v[106:109] offset:50688
	s_waitcnt lgkmcnt(0)
	s_barrier
	v_mfma_f32_32x32x16_bf16 v[16:31], v[110:113], v[118:121], v[16:31]
	v_mfma_f32_32x32x16_bf16 v[0:15], v[114:117], v[118:121], v[0:15]
	v_mfma_f32_32x32x16_bf16 v[16:31], v[46:49], v[58:61], v[16:31]
	v_mfma_f32_32x32x16_bf16 v[0:15], v[50:53], v[58:61], v[0:15]
	ds_read_b128 v[46:49], v36 offset:18432
	ds_read_b128 v[58:61], v36 offset:23040
	ds_read_b128 v[50:53], v33 offset:46080
	ds_read_b128 v[74:77], v36 offset:18464
	ds_read_b128 v[78:81], v36 offset:23072
	ds_read_b128 v[82:85], v33 offset:46112
	s_waitcnt lgkmcnt(3)
	v_mfma_f32_32x32x16_bf16 v[16:31], v[46:49], v[50:53], v[16:31]
	v_mfma_f32_32x32x16_bf16 v[0:15], v[58:61], v[50:53], v[0:15]
	global_load_dwordx4 v[46:49], v34, vcc offset:1152
	global_load_dwordx4 v[50:53], v35, vcc offset:1152
	global_load_dwordx4 v[58:61], v38, vcc offset:1152
	global_load_dwordx4 v[98:101], v39, vcc offset:1152
	global_load_dwordx4 v[102:105], v34, s[14:15]
	global_load_dwordx4 v[106:109], v35, s[14:15]
	ds_read_b128 v[110:113], v36 offset:18496
	ds_read_b128 v[114:117], v36 offset:23104
	ds_read_b128 v[118:121], v33 offset:46144
	s_waitcnt vmcnt(11)
	ds_write_b128 v32, v[62:65]
	s_waitcnt vmcnt(10)
	ds_write_b128 v32, v[66:69] offset:4608
	s_waitcnt vmcnt(9)
	ds_write_b128 v32, v[70:73] offset:9216
	s_waitcnt vmcnt(8)
	ds_write_b128 v32, v[86:89] offset:13824
	s_waitcnt lgkmcnt(7)
	v_mfma_f32_32x32x16_bf16 v[16:31], v[74:77], v[82:85], v[16:31]
	v_mfma_f32_32x32x16_bf16 v[0:15], v[78:81], v[82:85], v[0:15]
	ds_read_b128 v[62:65], v36 offset:18528
	ds_read_b128 v[66:69], v36 offset:23136
	ds_read_b128 v[70:73], v33 offset:46176
	s_waitcnt vmcnt(7)
	ds_write_b128 v32, v[90:93] offset:36864
	s_waitcnt vmcnt(6)
	ds_write_b128 v32, v[94:97] offset:41472
	s_waitcnt lgkmcnt(0)
	s_barrier
	v_mfma_f32_32x32x16_bf16 v[16:31], v[110:113], v[118:121], v[16:31]
	v_mfma_f32_32x32x16_bf16 v[0:15], v[114:117], v[118:121], v[0:15]
	v_mfma_f32_32x32x16_bf16 v[16:31], v[62:65], v[70:73], v[16:31]
	v_mfma_f32_32x32x16_bf16 v[0:15], v[66:69], v[70:73], v[0:15]
	ds_read_b128 v[62:65], v36
	ds_read_b128 v[70:73], v36 offset:4608
	ds_read_b128 v[66:69], v33 offset:36864
	ds_read_b128 v[74:77], v36 offset:32
	ds_read_b128 v[78:81], v36 offset:4640
	ds_read_b128 v[82:85], v33 offset:36896
	s_waitcnt lgkmcnt(3)
	v_mfma_f32_32x32x16_bf16 v[16:31], v[62:65], v[66:69], v[16:31]
	v_mfma_f32_32x32x16_bf16 v[0:15], v[70:73], v[66:69], v[0:15]
	global_load_dwordx4 v[62:65], v34, vcc offset:1280
	global_load_dwordx4 v[66:69], v35, vcc offset:1280
	global_load_dwordx4 v[70:73], v38, vcc offset:1280
	global_load_dwordx4 v[86:89], v39, vcc offset:1280
	global_load_dwordx4 v[90:93], v34, s[52:53]
	global_load_dwordx4 v[94:97], v35, s[52:53]
	ds_read_b128 v[110:113], v36 offset:64
	ds_read_b128 v[114:117], v36 offset:4672
	ds_read_b128 v[118:121], v33 offset:36928
	s_waitcnt vmcnt(11)
	ds_write_b128 v32, v[46:49] offset:18432
	s_waitcnt vmcnt(10)
	ds_write_b128 v32, v[50:53] offset:23040
	s_waitcnt vmcnt(9)
	ds_write_b128 v32, v[58:61] offset:27648
	s_waitcnt vmcnt(8)
	ds_write_b128 v32, v[98:101] offset:32256
	s_waitcnt lgkmcnt(7)
	v_mfma_f32_32x32x16_bf16 v[16:31], v[74:77], v[82:85], v[16:31]
	v_mfma_f32_32x32x16_bf16 v[0:15], v[78:81], v[82:85], v[0:15]
	ds_read_b128 v[46:49], v36 offset:96
	ds_read_b128 v[50:53], v36 offset:4704
	ds_read_b128 v[58:61], v33 offset:36960
	s_waitcnt vmcnt(7)
	ds_write_b128 v32, v[102:105] offset:46080
	s_waitcnt vmcnt(6)
	ds_write_b128 v32, v[106:109] offset:50688
	s_waitcnt lgkmcnt(0)
	s_barrier
	v_mfma_f32_32x32x16_bf16 v[16:31], v[110:113], v[118:121], v[16:31]
	v_mfma_f32_32x32x16_bf16 v[0:15], v[114:117], v[118:121], v[0:15]
	v_mfma_f32_32x32x16_bf16 v[16:31], v[46:49], v[58:61], v[16:31]
	v_mfma_f32_32x32x16_bf16 v[0:15], v[50:53], v[58:61], v[0:15]
	ds_read_b128 v[46:49], v36 offset:18432
	ds_read_b128 v[58:61], v36 offset:23040
	ds_read_b128 v[50:53], v33 offset:46080
	ds_read_b128 v[74:77], v36 offset:18464
	ds_read_b128 v[78:81], v36 offset:23072
	ds_read_b128 v[82:85], v33 offset:46112
	s_waitcnt lgkmcnt(3)
	v_mfma_f32_32x32x16_bf16 v[16:31], v[46:49], v[50:53], v[16:31]
	v_mfma_f32_32x32x16_bf16 v[0:15], v[58:61], v[50:53], v[0:15]
	global_load_dwordx4 v[46:49], v34, vcc offset:1408
	global_load_dwordx4 v[50:53], v35, vcc offset:1408
	global_load_dwordx4 v[58:61], v38, vcc offset:1408
	global_load_dwordx4 v[98:101], v39, vcc offset:1408
	global_load_dwordx4 v[102:105], v34, s[96:97]
	global_load_dwordx4 v[106:109], v35, s[96:97]
	ds_read_b128 v[110:113], v36 offset:18496
	ds_read_b128 v[114:117], v36 offset:23104
	ds_read_b128 v[118:121], v33 offset:46144
	s_waitcnt vmcnt(11)
	ds_write_b128 v32, v[62:65]
	s_waitcnt vmcnt(10)
	ds_write_b128 v32, v[66:69] offset:4608
	s_waitcnt vmcnt(9)
	ds_write_b128 v32, v[70:73] offset:9216
	s_waitcnt vmcnt(8)
	ds_write_b128 v32, v[86:89] offset:13824
	s_waitcnt lgkmcnt(7)
	v_mfma_f32_32x32x16_bf16 v[16:31], v[74:77], v[82:85], v[16:31]
	v_mfma_f32_32x32x16_bf16 v[0:15], v[78:81], v[82:85], v[0:15]
	ds_read_b128 v[62:65], v36 offset:18528
	ds_read_b128 v[66:69], v36 offset:23136
	ds_read_b128 v[70:73], v33 offset:46176
	s_waitcnt vmcnt(7)
	ds_write_b128 v32, v[90:93] offset:36864
	s_waitcnt vmcnt(6)
	ds_write_b128 v32, v[94:97] offset:41472
	s_waitcnt lgkmcnt(0)
	s_barrier
	v_mfma_f32_32x32x16_bf16 v[16:31], v[110:113], v[118:121], v[16:31]
	v_mfma_f32_32x32x16_bf16 v[0:15], v[114:117], v[118:121], v[0:15]
	v_mfma_f32_32x32x16_bf16 v[16:31], v[62:65], v[70:73], v[16:31]
	v_mfma_f32_32x32x16_bf16 v[0:15], v[66:69], v[70:73], v[0:15]
	ds_read_b128 v[62:65], v36
	ds_read_b128 v[70:73], v36 offset:4608
	ds_read_b128 v[66:69], v33 offset:36864
	ds_read_b128 v[74:77], v36 offset:32
	ds_read_b128 v[78:81], v36 offset:4640
	ds_read_b128 v[82:85], v33 offset:36896
	s_waitcnt lgkmcnt(3)
	v_mfma_f32_32x32x16_bf16 v[16:31], v[62:65], v[66:69], v[16:31]
	v_mfma_f32_32x32x16_bf16 v[0:15], v[70:73], v[66:69], v[0:15]
	global_load_dwordx4 v[62:65], v34, vcc offset:1536
	global_load_dwordx4 v[66:69], v35, vcc offset:1536
	global_load_dwordx4 v[70:73], v38, vcc offset:1536
	global_load_dwordx4 v[86:89], v39, vcc offset:1536
	global_load_dwordx4 v[90:93], v34, s[68:69]
	global_load_dwordx4 v[94:97], v35, s[68:69]
	ds_read_b128 v[110:113], v36 offset:64
	ds_read_b128 v[114:117], v36 offset:4672
	ds_read_b128 v[118:121], v33 offset:36928
	s_waitcnt vmcnt(11)
	ds_write_b128 v32, v[46:49] offset:18432
	s_waitcnt vmcnt(10)
	ds_write_b128 v32, v[50:53] offset:23040
	s_waitcnt vmcnt(9)
	ds_write_b128 v32, v[58:61] offset:27648
	s_waitcnt vmcnt(8)
	ds_write_b128 v32, v[98:101] offset:32256
	s_waitcnt lgkmcnt(7)
	v_mfma_f32_32x32x16_bf16 v[16:31], v[74:77], v[82:85], v[16:31]
	v_mfma_f32_32x32x16_bf16 v[0:15], v[78:81], v[82:85], v[0:15]
	ds_read_b128 v[46:49], v36 offset:96
	ds_read_b128 v[50:53], v36 offset:4704
	ds_read_b128 v[58:61], v33 offset:36960
	s_waitcnt vmcnt(7)
	ds_write_b128 v32, v[102:105] offset:46080
	s_waitcnt vmcnt(6)
	ds_write_b128 v32, v[106:109] offset:50688
	s_waitcnt lgkmcnt(0)
	s_barrier
	v_mfma_f32_32x32x16_bf16 v[16:31], v[110:113], v[118:121], v[16:31]
	v_mfma_f32_32x32x16_bf16 v[0:15], v[114:117], v[118:121], v[0:15]
	v_mfma_f32_32x32x16_bf16 v[16:31], v[46:49], v[58:61], v[16:31]
	v_mfma_f32_32x32x16_bf16 v[0:15], v[50:53], v[58:61], v[0:15]
	ds_read_b128 v[46:49], v36 offset:18432
	ds_read_b128 v[58:61], v36 offset:23040
	ds_read_b128 v[50:53], v33 offset:46080
	ds_read_b128 v[74:77], v36 offset:18464
	ds_read_b128 v[78:81], v36 offset:23072
	ds_read_b128 v[82:85], v33 offset:46112
	s_waitcnt lgkmcnt(3)
	v_mfma_f32_32x32x16_bf16 v[16:31], v[46:49], v[50:53], v[16:31]
	v_mfma_f32_32x32x16_bf16 v[0:15], v[58:61], v[50:53], v[0:15]
	global_load_dwordx4 v[46:49], v34, vcc offset:1664
	global_load_dwordx4 v[50:53], v35, vcc offset:1664
	global_load_dwordx4 v[58:61], v38, vcc offset:1664
	global_load_dwordx4 v[98:101], v39, vcc offset:1664
	global_load_dwordx4 v[102:105], v34, s[70:71]
	global_load_dwordx4 v[106:109], v35, s[70:71]
	ds_read_b128 v[110:113], v36 offset:18496
	ds_read_b128 v[114:117], v36 offset:23104
	ds_read_b128 v[118:121], v33 offset:46144
	s_waitcnt vmcnt(11)
	ds_write_b128 v32, v[62:65]
	s_waitcnt vmcnt(10)
	ds_write_b128 v32, v[66:69] offset:4608
	s_waitcnt vmcnt(9)
	ds_write_b128 v32, v[70:73] offset:9216
	s_waitcnt vmcnt(8)
	ds_write_b128 v32, v[86:89] offset:13824
	s_waitcnt lgkmcnt(7)
	v_mfma_f32_32x32x16_bf16 v[16:31], v[74:77], v[82:85], v[16:31]
	v_mfma_f32_32x32x16_bf16 v[0:15], v[78:81], v[82:85], v[0:15]
	ds_read_b128 v[62:65], v36 offset:18528
	ds_read_b128 v[66:69], v36 offset:23136
	ds_read_b128 v[70:73], v33 offset:46176
	s_waitcnt vmcnt(7)
	ds_write_b128 v32, v[90:93] offset:36864
	s_waitcnt vmcnt(6)
	ds_write_b128 v32, v[94:97] offset:41472
	s_waitcnt lgkmcnt(0)
	s_barrier
	v_mfma_f32_32x32x16_bf16 v[16:31], v[110:113], v[118:121], v[16:31]
	v_mfma_f32_32x32x16_bf16 v[0:15], v[114:117], v[118:121], v[0:15]
	v_mfma_f32_32x32x16_bf16 v[16:31], v[62:65], v[70:73], v[16:31]
	v_mfma_f32_32x32x16_bf16 v[0:15], v[66:69], v[70:73], v[0:15]
	ds_read_b128 v[62:65], v36
	ds_read_b128 v[70:73], v36 offset:4608
	ds_read_b128 v[66:69], v33 offset:36864
	ds_read_b128 v[74:77], v36 offset:32
	ds_read_b128 v[78:81], v36 offset:4640
	ds_read_b128 v[82:85], v33 offset:36896
	s_waitcnt lgkmcnt(3)
	v_mfma_f32_32x32x16_bf16 v[16:31], v[62:65], v[66:69], v[16:31]
	v_mfma_f32_32x32x16_bf16 v[0:15], v[70:73], v[66:69], v[0:15]
	global_load_dwordx4 v[62:65], v34, vcc offset:1792
	global_load_dwordx4 v[66:69], v35, vcc offset:1792
	global_load_dwordx4 v[70:73], v38, vcc offset:1792
	global_load_dwordx4 v[86:89], v39, vcc offset:1792
	global_load_dwordx4 v[90:93], v34, s[72:73]
	global_load_dwordx4 v[94:97], v35, s[72:73]
	ds_read_b128 v[110:113], v36 offset:64
	ds_read_b128 v[114:117], v36 offset:4672
	ds_read_b128 v[118:121], v33 offset:36928
	s_waitcnt vmcnt(11)
	ds_write_b128 v32, v[46:49] offset:18432
	s_waitcnt vmcnt(10)
	ds_write_b128 v32, v[50:53] offset:23040
	s_waitcnt vmcnt(9)
	ds_write_b128 v32, v[58:61] offset:27648
	s_waitcnt vmcnt(8)
	ds_write_b128 v32, v[98:101] offset:32256
	s_waitcnt lgkmcnt(7)
	v_mfma_f32_32x32x16_bf16 v[16:31], v[74:77], v[82:85], v[16:31]
	v_mfma_f32_32x32x16_bf16 v[0:15], v[78:81], v[82:85], v[0:15]
	ds_read_b128 v[46:49], v36 offset:96
	ds_read_b128 v[50:53], v36 offset:4704
	ds_read_b128 v[58:61], v33 offset:36960
	s_waitcnt vmcnt(7)
	ds_write_b128 v32, v[102:105] offset:46080
	s_waitcnt vmcnt(6)
	ds_write_b128 v32, v[106:109] offset:50688
	s_waitcnt lgkmcnt(0)
	s_barrier
	v_mfma_f32_32x32x16_bf16 v[16:31], v[110:113], v[118:121], v[16:31]
	v_mfma_f32_32x32x16_bf16 v[0:15], v[114:117], v[118:121], v[0:15]
	v_mfma_f32_32x32x16_bf16 v[16:31], v[46:49], v[58:61], v[16:31]
	v_mfma_f32_32x32x16_bf16 v[0:15], v[50:53], v[58:61], v[0:15]
	ds_read_b128 v[58:61], v36 offset:23040
	ds_read_b128 v[50:53], v33 offset:46080
	ds_read_b128 v[46:49], v36 offset:18432
	ds_read_b128 v[78:81], v36 offset:23072
	ds_read_b128 v[74:77], v36 offset:18464
	ds_read_b128 v[82:85], v33 offset:46112
	s_waitcnt lgkmcnt(4)
	v_mfma_f32_32x32x16_bf16 v[0:15], v[58:61], v[50:53], v[0:15]
	s_waitcnt lgkmcnt(3)
	v_mfma_f32_32x32x16_bf16 v[16:31], v[46:49], v[50:53], v[16:31]
	global_load_dwordx4 v[46:49], v34, vcc offset:1920
	global_load_dwordx4 v[50:53], v35, vcc offset:1920
	global_load_dwordx4 v[58:61], v38, vcc offset:1920
	global_load_dwordx4 v[98:101], v39, vcc offset:1920
	global_load_dwordx4 v[102:105], v34, s[74:75]
	global_load_dwordx4 v[106:109], v35, s[74:75]
	ds_read_b128 v[114:117], v36 offset:23104
	ds_read_b128 v[110:113], v36 offset:18496
	ds_read_b128 v[118:121], v33 offset:46144
	s_waitcnt vmcnt(11)
	ds_write_b128 v32, v[62:65]
	s_waitcnt vmcnt(10)
	ds_write_b128 v32, v[66:69] offset:4608
	s_waitcnt vmcnt(9)
	ds_write_b128 v32, v[70:73] offset:9216
	s_waitcnt vmcnt(8)
	ds_write_b128 v32, v[86:89] offset:13824
	s_waitcnt lgkmcnt(7)
	v_mfma_f32_32x32x16_bf16 v[0:15], v[78:81], v[82:85], v[0:15]
	ds_read_b128 v[66:69], v36 offset:23136
	ds_read_b128 v[62:65], v36 offset:18528
	ds_read_b128 v[70:73], v33 offset:46176
	s_waitcnt vmcnt(7)
	ds_write_b128 v32, v[90:93] offset:36864
	s_waitcnt vmcnt(6)
	ds_write_b128 v32, v[94:97] offset:41472
	s_waitcnt lgkmcnt(0)
	s_barrier
	v_mfma_f32_32x32x16_bf16 v[0:15], v[114:117], v[118:121], v[0:15]
	v_mfma_f32_32x32x16_bf16 v[0:15], v[66:69], v[70:73], v[0:15]
	ds_read_b128 v[66:69], v33 offset:36864
	v_mfma_f32_32x32x16_bf16 v[16:31], v[74:77], v[82:85], v[16:31]
	v_mfma_f32_32x32x16_bf16 v[16:31], v[110:113], v[118:121], v[16:31]
	v_mfma_f32_32x32x16_bf16 v[16:31], v[62:65], v[70:73], v[16:31]
	ds_read_b128 v[62:65], v36
	s_waitcnt lgkmcnt(0)
	v_mfma_f32_32x32x16_bf16 v[16:31], v[62:65], v[66:69], v[16:31]
	ds_read_b128 v[62:65], v36 offset:4608
	s_waitcnt lgkmcnt(0)
	v_mfma_f32_32x32x16_bf16 v[0:15], v[62:65], v[66:69], v[0:15]
	ds_read_b128 v[62:65], v36 offset:32
	ds_read_b128 v[66:69], v33 offset:36896
	s_waitcnt lgkmcnt(0)
	v_mfma_f32_32x32x16_bf16 v[16:31], v[62:65], v[66:69], v[16:31]
	ds_read_b128 v[62:65], v36 offset:4640
	s_waitcnt lgkmcnt(0)
	v_mfma_f32_32x32x16_bf16 v[0:15], v[62:65], v[66:69], v[0:15]
	ds_read_b128 v[62:65], v36 offset:64
	ds_read_b128 v[66:69], v33 offset:36928
	s_waitcnt lgkmcnt(0)
	v_mfma_f32_32x32x16_bf16 v[16:31], v[62:65], v[66:69], v[16:31]
	ds_read_b128 v[62:65], v36 offset:4672
	s_waitcnt vmcnt(3)
	ds_write_b128 v32, v[58:61] offset:27648
	s_waitcnt vmcnt(2)
	ds_write_b128 v32, v[98:101] offset:32256
	ds_write_b128 v32, v[46:49] offset:18432
	ds_write_b128 v32, v[50:53] offset:23040
	ds_read_b128 v[46:49], v36 offset:96
	ds_read_b128 v[50:53], v33 offset:36960
	s_waitcnt lgkmcnt(0)
	v_mfma_f32_32x32x16_bf16 v[16:31], v[46:49], v[50:53], v[16:31]
	ds_read_b128 v[46:49], v36 offset:4704
	v_add_u32_e32 v58, s41, v57
	v_add_u32_e32 v45, 0xffffe000, v58
	v_mfma_f32_32x32x16_bf16 v[0:15], v[62:65], v[66:69], v[0:15]
	s_waitcnt lgkmcnt(0)
	v_mfma_f32_32x32x16_bf16 v[0:15], v[46:49], v[50:53], v[0:15]
	s_waitcnt vmcnt(1)
	ds_write_b128 v32, v[102:105] offset:46080
	s_waitcnt vmcnt(0)
	ds_write_b128 v32, v[106:109] offset:50688
	s_waitcnt lgkmcnt(0)
	s_barrier
	ds_read_b128 v[46:49], v36 offset:18432
	ds_read_b128 v[50:53], v33 offset:46080
	s_waitcnt lgkmcnt(0)
	v_mfma_f32_32x32x16_bf16 v[16:31], v[46:49], v[50:53], v[16:31]
	ds_read_b128 v[46:49], v36 offset:23040
	s_waitcnt lgkmcnt(0)
	v_mfma_f32_32x32x16_bf16 v[0:15], v[46:49], v[50:53], v[0:15]
	ds_read_b128 v[46:49], v36 offset:18464
	ds_read_b128 v[50:53], v33 offset:46112
	s_waitcnt lgkmcnt(0)
	v_mfma_f32_32x32x16_bf16 v[16:31], v[46:49], v[50:53], v[16:31]
	ds_read_b128 v[46:49], v36 offset:23072
	s_waitcnt lgkmcnt(0)
	v_mfma_f32_32x32x16_bf16 v[0:15], v[46:49], v[50:53], v[0:15]
	ds_read_b128 v[46:49], v36 offset:18496
	ds_read_b128 v[50:53], v33 offset:46144
	ds_read_b128 v[32:35], v33 offset:46176
	s_waitcnt lgkmcnt(1)
	v_mfma_f32_32x32x16_bf16 v[16:31], v[46:49], v[50:53], v[16:31]
	ds_read_b128 v[46:49], v36 offset:23104
	s_waitcnt lgkmcnt(0)
	v_mfma_f32_32x32x16_bf16 v[0:15], v[46:49], v[50:53], v[0:15]
	ds_read_b128 v[46:49], v36 offset:18528
	ds_read_b128 v[36:39], v36 offset:23136
	s_waitcnt lgkmcnt(0)
	s_barrier
	v_mfma_f32_32x32x16_bf16 v[16:31], v[46:49], v[32:35], v[16:31]
	v_mfma_f32_32x32x16_bf16 v[0:15], v[36:39], v[32:35], v[0:15]
	v_readfirstlane_b32 s13, v186
	v_and_b32_e32 v32, 63, v186
	v_and_b32_e32 v33, 31, v32
	v_lshrrev_b32_e32 v34, 5, v32
	s_lshr_b32 s13, s13, 6
	s_and_b32 s32, s13, 1
	s_mul_i32 s80, s13, 0x1400
	s_lshr_b32 s13, s13, 1
	s_lshl_b32 s13, s13, 6
	s_add_i32 s33, s41, 0xffffe000
	s_add_i32 s81, s13, s33
	v_lshl_add_u32 v35, v34, 2, s81
	s_cmp_lg_u32 s32, 0
	s_cbranch_scc1 .Lp3a_gate
	v_and_b32_e32 v36, 15, v33
	v_lshlrev_b32_e32 v37, 6, v35
	v_lshl_add_u32 v37, v36, 2, v37
	v_xor_b32_e32 v38, 16, v32
	v_lshlrev_b32_e32 v38, 2, v38
	global_load_dword v84, v37, s[0:1]
	global_load_dword v116, v37, s[8:9]
	global_load_dword v85, v37, s[0:1] offset:64
	global_load_dword v117, v37, s[8:9] offset:64
	global_load_dword v86, v37, s[0:1] offset:128
	global_load_dword v118, v37, s[8:9] offset:128
	global_load_dword v87, v37, s[0:1] offset:192
	global_load_dword v119, v37, s[8:9] offset:192
	global_load_dword v88, v37, s[0:1] offset:512
	global_load_dword v120, v37, s[8:9] offset:512
	global_load_dword v89, v37, s[0:1] offset:576
	global_load_dword v121, v37, s[8:9] offset:576
	global_load_dword v90, v37, s[0:1] offset:640
	global_load_dword v122, v37, s[8:9] offset:640
	global_load_dword v91, v37, s[0:1] offset:704
	global_load_dword v123, v37, s[8:9] offset:704
	global_load_dword v92, v37, s[0:1] offset:1024
	global_load_dword v124, v37, s[8:9] offset:1024
	global_load_dword v93, v37, s[0:1] offset:1088
	global_load_dword v125, v37, s[8:9] offset:1088
	global_load_dword v94, v37, s[0:1] offset:1152
	global_load_dword v126, v37, s[8:9] offset:1152
	global_load_dword v95, v37, s[0:1] offset:1216
	global_load_dword v127, v37, s[8:9] offset:1216
	global_load_dword v96, v37, s[0:1] offset:1536
	global_load_dword v128, v37, s[8:9] offset:1536
	global_load_dword v97, v37, s[0:1] offset:1600
	global_load_dword v129, v37, s[8:9] offset:1600
	global_load_dword v98, v37, s[0:1] offset:1664
	global_load_dword v130, v37, s[8:9] offset:1664
	global_load_dword v99, v37, s[0:1] offset:1728
	global_load_dword v131, v37, s[8:9] offset:1728
	global_load_dword v100, v37, s[0:1] offset:2048
	global_load_dword v132, v37, s[8:9] offset:2048
	global_load_dword v101, v37, s[0:1] offset:2112
	global_load_dword v133, v37, s[8:9] offset:2112
	global_load_dword v102, v37, s[0:1] offset:2176
	global_load_dword v134, v37, s[8:9] offset:2176
	global_load_dword v103, v37, s[0:1] offset:2240
	global_load_dword v135, v37, s[8:9] offset:2240
	global_load_dword v104, v37, s[0:1] offset:2560
	global_load_dword v136, v37, s[8:9] offset:2560
	global_load_dword v105, v37, s[0:1] offset:2624
	global_load_dword v137, v37, s[8:9] offset:2624
	global_load_dword v106, v37, s[0:1] offset:2688
	global_load_dword v138, v37, s[8:9] offset:2688
	global_load_dword v107, v37, s[0:1] offset:2752
	global_load_dword v139, v37, s[8:9] offset:2752
	global_load_dword v108, v37, s[0:1] offset:3072
	global_load_dword v140, v37, s[8:9] offset:3072
	global_load_dword v109, v37, s[0:1] offset:3136
	global_load_dword v141, v37, s[8:9] offset:3136
	global_load_dword v110, v37, s[0:1] offset:3200
	global_load_dword v142, v37, s[8:9] offset:3200
	global_load_dword v111, v37, s[0:1] offset:3264
	global_load_dword v143, v37, s[8:9] offset:3264
	global_load_dword v112, v37, s[0:1] offset:3584
	global_load_dword v144, v37, s[8:9] offset:3584
	global_load_dword v113, v37, s[0:1] offset:3648
	global_load_dword v145, v37, s[8:9] offset:3648
	global_load_dword v114, v37, s[0:1] offset:3712
	global_load_dword v146, v37, s[8:9] offset:3712
	global_load_dword v115, v37, s[0:1] offset:3776
	global_load_dword v147, v37, s[8:9] offset:3776
	v_mul_u32_u24_e32 v76, 0x140, v34
	v_lshl_add_u32 v76, v33, 1, v76
	v_add_u32_e32 v76, s80, v76
	v_lshrrev_b32_e32 v77, 2, v32
	v_and_b32_e32 v78, 3, v32
	v_mul_u32_u24_e32 v80, 0x50, v77
	v_lshl_add_u32 v80, v78, 4, v80
	v_add_u32_e32 v80, s80, v80
	s_and_b32 s32, s81, 0x1fff
	v_add_u32_e32 v39, s32, v77
	v_mul_u32_u24_e32 v39, 0xc0, v39
	v_lshl_add_u32 v39, v78, 4, v39
	v_add_u32_e32 v39, 0x80, v39
	s_lshr_b32 s13, s33, 13
	s_mul_i32 s13, s13, 0xc00000
	s_add_u32 s13, s13, 0xb200000
	s_add_u32 s78, s88, s13
	s_addc_u32 s79, s89, 0
	ds_bpermute_b32 v148, v38, v16
	ds_bpermute_b32 v149, v38, v17
	ds_bpermute_b32 v150, v38, v18
	ds_bpermute_b32 v151, v38, v19
	ds_bpermute_b32 v152, v38, v20
	ds_bpermute_b32 v153, v38, v21
	ds_bpermute_b32 v154, v38, v22
	ds_bpermute_b32 v155, v38, v23
	s_waitcnt vmcnt(0) lgkmcnt(0)
	v_mul_f32_e32 v46, v116, v148
	v_cndmask_b32_e64 v46, v46, -v46, s[6:7]
	v_fmac_f32_e32 v46, v16, v84
	v_cvt_pk_bf16_f32 v46, v46, v46
	ds_write_b16 v76, v46
	v_mul_f32_e32 v47, v117, v149
	v_cndmask_b32_e64 v47, v47, -v47, s[6:7]
	v_fmac_f32_e32 v47, v17, v85
	v_cvt_pk_bf16_f32 v47, v47, v47
	ds_write_b16 v76, v47 offset:80
	v_mul_f32_e32 v48, v118, v150
	v_cndmask_b32_e64 v48, v48, -v48, s[6:7]
	v_fmac_f32_e32 v48, v18, v86
	v_cvt_pk_bf16_f32 v48, v48, v48
	ds_write_b16 v76, v48 offset:160
	v_mul_f32_e32 v49, v119, v151
	v_cndmask_b32_e64 v49, v49, -v49, s[6:7]
	v_fmac_f32_e32 v49, v19, v87
	v_cvt_pk_bf16_f32 v49, v49, v49
	ds_write_b16 v76, v49 offset:240
	v_mul_f32_e32 v46, v120, v152
	v_cndmask_b32_e64 v46, v46, -v46, s[6:7]
	v_fmac_f32_e32 v46, v20, v88
	v_cvt_pk_bf16_f32 v46, v46, v46
	ds_write_b16 v76, v46 offset:640
	v_mul_f32_e32 v47, v121, v153
	v_cndmask_b32_e64 v47, v47, -v47, s[6:7]
	v_fmac_f32_e32 v47, v21, v89
	v_cvt_pk_bf16_f32 v47, v47, v47
	ds_write_b16 v76, v47 offset:720
	v_mul_f32_e32 v48, v122, v154
	v_cndmask_b32_e64 v48, v48, -v48, s[6:7]
	v_fmac_f32_e32 v48, v22, v90
	v_cvt_pk_bf16_f32 v48, v48, v48
	ds_write_b16 v76, v48 offset:800
	v_mul_f32_e32 v49, v123, v155
	v_cndmask_b32_e64 v49, v49, -v49, s[6:7]
	v_fmac_f32_e32 v49, v23, v91
	v_cvt_pk_bf16_f32 v49, v49, v49
	ds_write_b16 v76, v49 offset:880
	ds_bpermute_b32 v148, v38, v24
	ds_bpermute_b32 v149, v38, v25
	ds_bpermute_b32 v150, v38, v26
	ds_bpermute_b32 v151, v38, v27
	ds_bpermute_b32 v152, v38, v28
	ds_bpermute_b32 v153, v38, v29
	ds_bpermute_b32 v154, v38, v30
	ds_bpermute_b32 v155, v38, v31
	s_waitcnt lgkmcnt(0)
	v_mul_f32_e32 v46, v124, v148
	v_cndmask_b32_e64 v46, v46, -v46, s[6:7]
	v_fmac_f32_e32 v46, v24, v92
	v_cvt_pk_bf16_f32 v46, v46, v46
	ds_write_b16 v76, v46 offset:1280
	v_mul_f32_e32 v47, v125, v149
	v_cndmask_b32_e64 v47, v47, -v47, s[6:7]
	v_fmac_f32_e32 v47, v25, v93
	v_cvt_pk_bf16_f32 v47, v47, v47
	ds_write_b16 v76, v47 offset:1360
	v_mul_f32_e32 v48, v126, v150
	v_cndmask_b32_e64 v48, v48, -v48, s[6:7]
	v_fmac_f32_e32 v48, v26, v94
	v_cvt_pk_bf16_f32 v48, v48, v48
	ds_write_b16 v76, v48 offset:1440
	v_mul_f32_e32 v49, v127, v151
	v_cndmask_b32_e64 v49, v49, -v49, s[6:7]
	v_fmac_f32_e32 v49, v27, v95
	v_cvt_pk_bf16_f32 v49, v49, v49
	ds_write_b16 v76, v49 offset:1520
	v_mul_f32_e32 v46, v128, v152
	v_cndmask_b32_e64 v46, v46, -v46, s[6:7]
	v_fmac_f32_e32 v46, v28, v96
	v_cvt_pk_bf16_f32 v46, v46, v46
	ds_write_b16 v76, v46 offset:1920
	v_mul_f32_e32 v47, v129, v153
	v_cndmask_b32_e64 v47, v47, -v47, s[6:7]
	v_fmac_f32_e32 v47, v29, v97
	v_cvt_pk_bf16_f32 v47, v47, v47
	ds_write_b16 v76, v47 offset:2000
	v_mul_f32_e32 v48, v130, v154
	v_cndmask_b32_e64 v48, v48, -v48, s[6:7]
	v_fmac_f32_e32 v48, v30, v98
	v_cvt_pk_bf16_f32 v48, v48, v48
	ds_write_b16 v76, v48 offset:2080
	v_mul_f32_e32 v49, v131, v155
	v_cndmask_b32_e64 v49, v49, -v49, s[6:7]
	v_fmac_f32_e32 v49, v31, v99
	v_cvt_pk_bf16_f32 v49, v49, v49
	ds_write_b16 v76, v49 offset:2160
	ds_bpermute_b32 v148, v38, v0
	ds_bpermute_b32 v149, v38, v1
	ds_bpermute_b32 v150, v38, v2
	ds_bpermute_b32 v151, v38, v3
	ds_bpermute_b32 v152, v38, v4
	ds_bpermute_b32 v153, v38, v5
	ds_bpermute_b32 v154, v38, v6
	ds_bpermute_b32 v155, v38, v7
	s_waitcnt lgkmcnt(0)
	v_mul_f32_e32 v46, v132, v148
	v_cndmask_b32_e64 v46, v46, -v46, s[6:7]
	v_fmac_f32_e32 v46, v0, v100
	v_cvt_pk_bf16_f32 v46, v46, v46
	ds_write_b16 v76, v46 offset:2560
	v_mul_f32_e32 v47, v133, v149
	v_cndmask_b32_e64 v47, v47, -v47, s[6:7]
	v_fmac_f32_e32 v47, v1, v101
	v_cvt_pk_bf16_f32 v47, v47, v47
	ds_write_b16 v76, v47 offset:2640
	v_mul_f32_e32 v48, v134, v150
	v_cndmask_b32_e64 v48, v48, -v48, s[6:7]
	v_fmac_f32_e32 v48, v2, v102
	v_cvt_pk_bf16_f32 v48, v48, v48
	ds_write_b16 v76, v48 offset:2720
	v_mul_f32_e32 v49, v135, v151
	v_cndmask_b32_e64 v49, v49, -v49, s[6:7]
	v_fmac_f32_e32 v49, v3, v103
	v_cvt_pk_bf16_f32 v49, v49, v49
	ds_write_b16 v76, v49 offset:2800
	v_mul_f32_e32 v46, v136, v152
	v_cndmask_b32_e64 v46, v46, -v46, s[6:7]
	v_fmac_f32_e32 v46, v4, v104
	v_cvt_pk_bf16_f32 v46, v46, v46
	ds_write_b16 v76, v46 offset:3200
	v_mul_f32_e32 v47, v137, v153
	v_cndmask_b32_e64 v47, v47, -v47, s[6:7]
	v_fmac_f32_e32 v47, v5, v105
	v_cvt_pk_bf16_f32 v47, v47, v47
	ds_write_b16 v76, v47 offset:3280
	v_mul_f32_e32 v48, v138, v154
	v_cndmask_b32_e64 v48, v48, -v48, s[6:7]
	v_fmac_f32_e32 v48, v6, v106
	v_cvt_pk_bf16_f32 v48, v48, v48
	ds_write_b16 v76, v48 offset:3360
	v_mul_f32_e32 v49, v139, v155
	v_cndmask_b32_e64 v49, v49, -v49, s[6:7]
	v_fmac_f32_e32 v49, v7, v107
	v_cvt_pk_bf16_f32 v49, v49, v49
	ds_write_b16 v76, v49 offset:3440
	ds_bpermute_b32 v148, v38, v8
	ds_bpermute_b32 v149, v38, v9
	ds_bpermute_b32 v150, v38, v10
	ds_bpermute_b32 v151, v38, v11
	ds_bpermute_b32 v152, v38, v12
	ds_bpermute_b32 v153, v38, v13
	ds_bpermute_b32 v154, v38, v14
	ds_bpermute_b32 v155, v38, v15
	s_waitcnt lgkmcnt(0)
	v_mul_f32_e32 v46, v140, v148
	v_cndmask_b32_e64 v46, v46, -v46, s[6:7]
	v_fmac_f32_e32 v46, v8, v108
	v_cvt_pk_bf16_f32 v46, v46, v46
	ds_write_b16 v76, v46 offset:3840
	v_mul_f32_e32 v47, v141, v149
	v_cndmask_b32_e64 v47, v47, -v47, s[6:7]
	v_fmac_f32_e32 v47, v9, v109
	v_cvt_pk_bf16_f32 v47, v47, v47
	ds_write_b16 v76, v47 offset:3920
	v_mul_f32_e32 v48, v142, v150
	v_cndmask_b32_e64 v48, v48, -v48, s[6:7]
	v_fmac_f32_e32 v48, v10, v110
	v_cvt_pk_bf16_f32 v48, v48, v48
	ds_write_b16 v76, v48 offset:4000
	v_mul_f32_e32 v49, v143, v151
	v_cndmask_b32_e64 v49, v49, -v49, s[6:7]
	v_fmac_f32_e32 v49, v11, v111
	v_cvt_pk_bf16_f32 v49, v49, v49
	ds_write_b16 v76, v49 offset:4080
	v_mul_f32_e32 v46, v144, v152
	v_cndmask_b32_e64 v46, v46, -v46, s[6:7]
	v_fmac_f32_e32 v46, v12, v112
	v_cvt_pk_bf16_f32 v46, v46, v46
	ds_write_b16 v76, v46 offset:4480
	v_mul_f32_e32 v47, v145, v153
	v_cndmask_b32_e64 v47, v47, -v47, s[6:7]
	v_fmac_f32_e32 v47, v13, v113
	v_cvt_pk_bf16_f32 v47, v47, v47
	ds_write_b16 v76, v47 offset:4560
	v_mul_f32_e32 v48, v146, v154
	v_cndmask_b32_e64 v48, v48, -v48, s[6:7]
	v_fmac_f32_e32 v48, v14, v114
	v_cvt_pk_bf16_f32 v48, v48, v48
	ds_write_b16 v76, v48 offset:4640
	v_mul_f32_e32 v49, v147, v155
	v_cndmask_b32_e64 v49, v49, -v49, s[6:7]
	v_fmac_f32_e32 v49, v15, v115
	v_cvt_pk_bf16_f32 v49, v49, v49
	ds_write_b16 v76, v49 offset:4720
	s_waitcnt lgkmcnt(0)
	ds_read_b128 v[60:63], v80
	ds_read_b128 v[64:67], v80 offset:1280
	ds_read_b128 v[68:71], v80 offset:2560
	ds_read_b128 v[72:75], v80 offset:3840
	s_waitcnt lgkmcnt(0)
	global_store_dwordx4 v39, v[60:63], s[78:79]
	v_add_u32_e32 v51, 0xc00, v39
	global_store_dwordx4 v51, v[64:67], s[78:79]
	v_add_u32_e32 v50, 0x1800, v39
	global_store_dwordx4 v50, v[68:71], s[78:79]
	v_add_u32_e32 v51, 0x2400, v39
	global_store_dwordx4 v51, v[72:75], s[78:79]
	v_add_u32_e32 v50, 0x180000, v39
	global_store_dwordx4 v50, v[60:63], s[78:79]
	v_add_u32_e32 v51, 0x180c00, v39
	global_store_dwordx4 v51, v[64:67], s[78:79]
	v_add_u32_e32 v50, 0x181800, v39
	global_store_dwordx4 v50, v[68:71], s[78:79]
	v_add_u32_e32 v51, 0x182400, v39
	global_store_dwordx4 v51, v[72:75], s[78:79]
	v_add_u32_e32 v50, 0x300000, v39
	global_store_dwordx4 v50, v[60:63], s[78:79]
	v_add_u32_e32 v51, 0x300c00, v39
	global_store_dwordx4 v51, v[64:67], s[78:79]
	v_add_u32_e32 v50, 0x301800, v39
	global_store_dwordx4 v50, v[68:71], s[78:79]
	v_add_u32_e32 v51, 0x302400, v39
	global_store_dwordx4 v51, v[72:75], s[78:79]
	v_add_u32_e32 v50, 0x480000, v39
	global_store_dwordx4 v50, v[60:63], s[78:79]
	v_add_u32_e32 v51, 0x480c00, v39
	global_store_dwordx4 v51, v[64:67], s[78:79]
	v_add_u32_e32 v50, 0x481800, v39
	global_store_dwordx4 v50, v[68:71], s[78:79]
	v_add_u32_e32 v51, 0x482400, v39
	global_store_dwordx4 v51, v[72:75], s[78:79]
	v_add_u32_e32 v50, 0x600000, v39
	global_store_dwordx4 v50, v[60:63], s[78:79]
	v_add_u32_e32 v51, 0x600c00, v39
	global_store_dwordx4 v51, v[64:67], s[78:79]
	v_add_u32_e32 v50, 0x601800, v39
	global_store_dwordx4 v50, v[68:71], s[78:79]
	v_add_u32_e32 v51, 0x602400, v39
	global_store_dwordx4 v51, v[72:75], s[78:79]
	v_add_u32_e32 v50, 0x780000, v39
	global_store_dwordx4 v50, v[60:63], s[78:79]
	v_add_u32_e32 v51, 0x780c00, v39
	global_store_dwordx4 v51, v[64:67], s[78:79]
	v_add_u32_e32 v50, 0x781800, v39
	global_store_dwordx4 v50, v[68:71], s[78:79]
	v_add_u32_e32 v51, 0x782400, v39
	global_store_dwordx4 v51, v[72:75], s[78:79]
	v_add_u32_e32 v50, 0x900000, v39
	global_store_dwordx4 v50, v[60:63], s[78:79]
	v_add_u32_e32 v51, 0x900c00, v39
	global_store_dwordx4 v51, v[64:67], s[78:79]
	v_add_u32_e32 v50, 0x901800, v39
	global_store_dwordx4 v50, v[68:71], s[78:79]
	v_add_u32_e32 v51, 0x902400, v39
	global_store_dwordx4 v51, v[72:75], s[78:79]
	v_add_u32_e32 v50, 0xa80000, v39
	global_store_dwordx4 v50, v[60:63], s[78:79]
	v_add_u32_e32 v51, 0xa80c00, v39
	global_store_dwordx4 v51, v[64:67], s[78:79]
	v_add_u32_e32 v50, 0xa81800, v39
	global_store_dwordx4 v50, v[68:71], s[78:79]
	v_add_u32_e32 v51, 0xa82400, v39
	global_store_dwordx4 v51, v[72:75], s[78:79]
	s_branch .Lp3a_done
